# rg_b chunk carry composed in parallel by the 8 waves and exchanged through LDS, on top of the P7 static-priority version
# baseline (speedup 1.0000x reference)
; __device__ __forceinline__ float bf2f(unsigned h) { return __uint_as_float(h << 16); }
; __device__ __forceinline__ unsigned pk2(float lo, float hi) { return f2bf(lo) | (f2bf(hi) << 16); }
; __device__ __forceinline__ float sigmf(float x) { return __builtin_amdgcn_rcpf(1.0f + __expf(-x)); }
; __device__ __forceinline__ void rg_b_unit(const Params& p, int unit) {
;     ...
;     for (int tq = 0; tq < 8; ++tq) { const int t = 8 * tq + r8; const size_t o = (size_t)(n * 64 + t) * D;
;         const u32x4 hv = __builtin_nontemporal_load((const u32x4*)(HL + o)), pv = __builtin_nontemporal_load((const u32x4*)(PC + o)), gv = __builtin_nontemporal_load((const u32x4*)(Z + (size_t)t * ZW + 1024)); u32x4 ov;
; #pragma unroll
;         for (int c = 0; c < 4; ++c) { const float h0 = bf2f(hv[c] & 0xffffu) + bf2f(pv[c] & 0xffffu) * carry[2 * c], h1 = bf2f(hv[c] >> 16) + bf2f(pv[c] >> 16) * carry[2 * c + 1];
;             const float g0 = bf2f(gv[c] & 0xffffu), g1 = bf2f(gv[c] >> 16); ov[c] = pk2(h0 * g0 * sigmf(g0), h1 * g1 * sigmf(g1)); }
;         *(u32x4*)(Z + (size_t)t * ZW) = ov; }
.LBB0_218:
	v_lshl_add_u64 v[24:25], v[22:23], 0, v[4:5]
	v_add_co_u32_e64 v66, s[4:5], s31, v24
	v_lshl_add_u64 v[28:29], v[14:15], 0, v[4:5]
	s_nop 0
	v_addc_co_u32_e64 v67, s[4:5], 0, v25, s[4:5]
	v_add_co_u32_e64 v42, s[4:5], s34, v28
	v_lshl_add_u64 v[30:31], v[20:21], 0, v[4:5]
	s_nop 0
	v_addc_co_u32_e64 v43, s[4:5], 0, v29, s[4:5]
	v_add_co_u32_e64 v40, s[4:5], s31, v30
	v_lshl_add_u64 v[32:33], v[16:17], 0, v[4:5]
	s_nop 0
	v_addc_co_u32_e64 v41, s[4:5], 0, v31, s[4:5]
	v_add_co_u32_e64 v38, s[4:5], s35, v28
	v_lshl_add_u64 v[26:27], v[18:19], 0, v[4:5]
	s_nop 0
	v_addc_co_u32_e64 v39, s[4:5], 0, v29, s[4:5]
	v_add_co_u32_e64 v36, s[4:5], s31, v32
	global_load_dwordx4 v[46:49], v[26:27], off nt
	v_add_co_u32_e32 v26, vcc, 0x2000000, v26
	v_addc_co_u32_e64 v37, s[4:5], 0, v33, s[4:5]
	v_add_co_u32_e64 v34, s[4:5], s36, v28
	v_addc_co_u32_e32 v27, vcc, 0, v27, vcc
	s_nop 0
	v_addc_co_u32_e64 v35, s[4:5], 0, v29, s[4:5]
	global_load_dwordx4 v[50:53], v[38:39], off offset:2048 nt
	global_load_dwordx4 v[0:3], v[34:35], off offset:2048 nt
	v_add_co_u32_e32 v68, vcc, 0x400000, v28
	global_load_dwordx4 v[54:57], v[26:27], off nt
	s_nop 0
	v_addc_co_u32_e32 v69, vcc, 0, v29, vcc
	global_load_dwordx4 v[58:61], v[68:69], off offset:2048 nt
	global_load_dwordx4 v[62:65], v[42:43], off offset:2048 nt
	s_add_i32 s10, s10, -4
	v_lshl_add_u64 v[14:15], v[14:15], 0, s[14:15]
	v_lshl_add_u64 v[16:17], v[16:17], 0, s[18:19]
	v_lshl_add_u64 v[18:19], v[18:19], 0, s[18:19]
	v_lshl_add_u64 v[20:21], v[20:21], 0, s[18:19]
	v_lshl_add_u64 v[22:23], v[22:23], 0, s[18:19]
	s_cmp_lg_u32 s10, 0
	s_waitcnt vmcnt(5)
	v_lshlrev_b32_e32 v71, 16, v47
	v_lshlrev_b32_e32 v70, 16, v46
	v_and_b32_e32 v47, 0xffff0000, v47
	v_and_b32_e32 v46, 0xffff0000, v46
	v_lshlrev_b32_e32 v73, 16, v49
	v_lshlrev_b32_e32 v72, 16, v48
	v_and_b32_e32 v49, 0xffff0000, v49
	v_and_b32_e32 v48, 0xffff0000, v48
	s_waitcnt vmcnt(4)
	v_lshlrev_b32_e32 v75, 16, v51
	v_lshlrev_b32_e32 v74, 16, v50
	v_and_b32_e32 v77, 0xffff0000, v51
	v_and_b32_e32 v76, 0xffff0000, v50
	v_lshlrev_b32_e32 v79, 16, v53
	v_lshlrev_b32_e32 v78, 16, v52
	v_and_b32_e32 v81, 0xffff0000, v53
	v_and_b32_e32 v80, 0xffff0000, v52
	s_waitcnt vmcnt(2)
	v_lshlrev_b32_e32 v51, 16, v55
	v_lshlrev_b32_e32 v50, 16, v54
	v_and_b32_e32 v53, 0xffff0000, v55
	v_and_b32_e32 v52, 0xffff0000, v54
	v_lshlrev_b32_e32 v55, 16, v57
	v_lshlrev_b32_e32 v54, 16, v56
	v_mul_f32_e32 v28, 0xbfb8aa3b, v74
	v_mul_f32_e32 v84, 0xbfb8aa3b, v76
	v_mul_f32_e32 v85, 0xbfb8aa3b, v75
	v_mul_f32_e32 v86, 0xbfb8aa3b, v77
	v_mul_f32_e32 v87, 0xbfb8aa3b, v78
	v_mul_f32_e32 v88, 0xbfb8aa3b, v80
	v_mul_f32_e32 v89, 0xbfb8aa3b, v79
	v_mul_f32_e32 v90, 0xbfb8aa3b, v81
	s_waitcnt vmcnt(1)
	v_lshlrev_b32_e32 v83, 16, v59
	v_lshlrev_b32_e32 v82, 16, v58
	v_and_b32_e32 v59, 0xffff0000, v59
	v_and_b32_e32 v58, 0xffff0000, v58
	v_pk_fma_f32 v[50:51], v[8:9], v[50:51], v[70:71]
	v_pk_fma_f32 v[46:47], v[10:11], v[52:53], v[46:47]
	v_lshlrev_b32_e32 v53, 16, v61
	v_lshlrev_b32_e32 v52, 16, v60
	v_and_b32_e32 v61, 0xffff0000, v61
	v_and_b32_e32 v60, 0xffff0000, v60
	v_pk_fma_f32 v[54:55], v[6:7], v[54:55], v[72:73]
	v_exp_f32_e32 v28, v28
	v_exp_f32_e32 v72, v84
	v_exp_f32_e32 v73, v85
	v_exp_f32_e32 v84, v86
	v_exp_f32_e32 v85, v87
	v_exp_f32_e32 v86, v88
	v_exp_f32_e32 v87, v89
	v_exp_f32_e32 v88, v90
	v_mul_f32_e32 v89, 0xbfb8aa3b, v82
	v_mul_f32_e32 v90, 0xbfb8aa3b, v58
	v_pk_mul_f32 v[50:51], v[50:51], v[82:83]
	v_mul_f32_e32 v82, 0xbfb8aa3b, v83
	v_pk_mul_f32 v[46:47], v[46:47], v[58:59]
	v_mul_f32_e32 v58, 0xbfb8aa3b, v59
	v_mul_f32_e32 v59, 0xbfb8aa3b, v52
	v_mul_f32_e32 v83, 0xbfb8aa3b, v60
	v_pk_mul_f32 v[54:55], v[54:55], v[52:53]
	v_mul_f32_e32 v52, 0xbfb8aa3b, v53
	v_mul_f32_e32 v53, 0xbfb8aa3b, v61
	v_and_b32_e32 v57, 0xffff0000, v57
	v_and_b32_e32 v56, 0xffff0000, v56
	v_exp_f32_e32 v89, v89
	v_exp_f32_e32 v90, v90
	v_exp_f32_e32 v97, v82
	v_exp_f32_e32 v98, v58
	v_exp_f32_e32 v99, v59
	v_exp_f32_e32 v100, v83
	v_exp_f32_e32 v52, v52
	v_exp_f32_e32 v53, v53
	v_pk_fma_f32 v[48:49], v[12:13], v[56:57], v[48:49]
	s_waitcnt vmcnt(0)
	v_lshlrev_b32_e32 v56, 16, v62
	v_and_b32_e32 v62, 0xffff0000, v62
	v_pk_mul_f32 v[48:49], v[48:49], v[60:61]
	v_mul_f32_e32 v61, 0xbfb8aa3b, v62
	v_mul_f32_e32 v60, 0xbfb8aa3b, v56
	v_exp_f32_e32 v102, v61
	v_add_f32_e32 v28, 1.0, v28
	v_add_f32_e32 v59, 1.0, v72
	v_add_f32_e32 v61, 1.0, v73
	v_add_f32_e32 v72, 1.0, v84
	v_add_f32_e32 v73, 1.0, v85
	v_add_f32_e32 v83, 1.0, v87
	v_add_f32_e32 v84, 1.0, v88
	v_exp_f32_e32 v101, v60
	v_add_f32_e32 v82, 1.0, v86
	v_rcp_f32_e32 v58, v28
	v_rcp_f32_e32 v60, v59
	v_rcp_f32_e32 v59, v61
	v_rcp_f32_e32 v61, v72
	v_rcp_f32_e32 v72, v73
	v_rcp_f32_e32 v73, v83
	v_rcp_f32_e32 v83, v84
	v_add_f32_e32 v28, 1.0, v89
	v_add_f32_e32 v84, 1.0, v90
	v_add_f32_e32 v85, 1.0, v97
	v_add_f32_e32 v86, 1.0, v98
	v_add_f32_e32 v87, 1.0, v99
	v_add_f32_e32 v88, 1.0, v100
	v_add_f32_e32 v89, 1.0, v52
	v_add_f32_e32 v90, 1.0, v53
	v_rcp_f32_e32 v52, v28
	v_rcp_f32_e32 v53, v85
	v_rcp_f32_e32 v85, v86
	v_rcp_f32_e32 v86, v87
	v_rcp_f32_e32 v88, v88
	v_rcp_f32_e32 v87, v89
	v_rcp_f32_e32 v89, v90
	v_rcp_f32_e32 v84, v84
	v_pk_mul_f32 v[50:51], v[50:51], v[52:53]
	v_pk_mul_f32 v[52:53], v[54:55], v[86:87]
	v_pk_mul_f32 v[48:49], v[48:49], v[88:89]
	v_pk_mul_f32 v[46:47], v[46:47], v[84:85]
	v_bfe_u32 v28, v49, 16, 1
	v_bfe_u32 v85, v50, 16, 1
	v_bfe_u32 v86, v51, 16, 1
	v_bfe_u32 v87, v52, 16, 1
	v_bfe_u32 v88, v53, 16, 1
	v_bfe_u32 v54, v48, 16, 1
	v_bfe_u32 v55, v47, 16, 1
	v_bfe_u32 v84, v46, 16, 1
	v_add3_u32 v28, v49, v28, s33
	v_add3_u32 v49, v53, v88, s33
	v_add3_u32 v52, v52, v87, s33
; __device__ __forceinline__ float bf2f(unsigned h) { return __uint_as_float(h << 16); }
; __device__ __forceinline__ unsigned pk2(float lo, float hi) { return f2bf(lo) | (f2bf(hi) << 16); }
; __device__ __forceinline__ float sigmf(float x) { return __builtin_amdgcn_rcpf(1.0f + __expf(-x)); }
; __device__ __forceinline__ void rg_b_unit(const Params& p, int unit) {
;     ...
; #pragma unroll 4
;     for (int tq = 0; tq < 8; ++tq) { const int t = 8 * tq + r8; const size_t o = (size_t)(n * 64 + t) * D;
;         const u32x4 hv = __builtin_nontemporal_load((const u32x4*)(HL + o)), pv = __builtin_nontemporal_load((const u32x4*)(PC + o)), gv = __builtin_nontemporal_load((const u32x4*)(Z + (size_t)t * ZW + 1024)); u32x4 ov;
; #pragma unroll
;         for (int c = 0; c < 4; ++c) { const float h0 = bf2f(hv[c] & 0xffffu) + bf2f(pv[c] & 0xffffu) * carry[2 * c], h1 = bf2f(hv[c] >> 16) + bf2f(pv[c] >> 16) * carry[2 * c + 1];
;             const float g0 = bf2f(gv[c] & 0xffffu), g1 = bf2f(gv[c] >> 16); ov[c] = pk2(h0 * g0 * sigmf(g0), h1 * g1 * sigmf(g1)); }
;         *(u32x4*)(Z + (size_t)t * ZW) = ov; }
	v_add3_u32 v51, v51, v86, s33
	v_add3_u32 v50, v50, v85, s33
	v_add3_u32 v46, v46, v84, s33
	v_add3_u32 v47, v47, v55, s33
	v_add3_u32 v48, v48, v54, s33
	v_lshrrev_b32_e32 v50, 16, v50
	v_lshrrev_b32_e32 v51, 16, v51
	v_lshrrev_b32_e32 v52, 16, v52
	v_lshrrev_b32_e32 v49, 16, v49
	v_and_or_b32 v49, v28, s29, v49
	v_and_or_b32 v48, v48, s29, v52
	v_and_or_b32 v47, v47, s29, v51
	v_and_or_b32 v46, v46, s29, v50
	global_store_dwordx4 v[68:69], v[46:49], off
	global_load_dwordx4 v[46:49], v[24:25], off nt
	s_nop 0
	global_load_dwordx4 v[50:53], v[66:67], off nt
	v_lshlrev_b32_e32 v57, 16, v63
	v_lshlrev_b32_e32 v71, 16, v65
	v_lshlrev_b32_e32 v70, 16, v64
	v_and_b32_e32 v65, 0xffff0000, v65
	v_and_b32_e32 v64, 0xffff0000, v64
	v_and_b32_e32 v63, 0xffff0000, v63
	v_mul_f32_e32 v91, 0xbfb8aa3b, v57
	v_mul_f32_e32 v93, 0xbfb8aa3b, v70
	v_mul_f32_e32 v94, 0xbfb8aa3b, v64
	v_mul_f32_e32 v95, 0xbfb8aa3b, v71
	v_mul_f32_e32 v96, 0xbfb8aa3b, v65
	v_mul_f32_e32 v92, 0xbfb8aa3b, v63
	v_exp_f32_e32 v91, v91
	v_exp_f32_e32 v93, v93
	v_exp_f32_e32 v94, v94
	v_exp_f32_e32 v95, v95
	v_exp_f32_e32 v96, v96
	v_exp_f32_e32 v92, v92
	v_add_f32_e32 v97, 1.0, v101
	v_add_f32_e32 v98, 1.0, v102
	v_add_f32_e32 v91, 1.0, v91
	v_add_f32_e32 v100, 1.0, v93
	v_add_f32_e32 v101, 1.0, v94
	v_add_f32_e32 v95, 1.0, v95
	v_add_f32_e32 v102, 1.0, v96
	v_add_f32_e32 v99, 1.0, v92
	v_rcp_f32_e32 v90, v97
	v_rcp_f32_e32 v91, v91
	v_rcp_f32_e32 v94, v100
	v_rcp_f32_e32 v96, v101
	v_rcp_f32_e32 v95, v95
	v_rcp_f32_e32 v97, v102
	v_rcp_f32_e32 v92, v98
	v_rcp_f32_e32 v93, v99
	v_rcp_f32_e32 v82, v82
	v_lshlrev_b32_e32 v27, 16, v1
	v_lshlrev_b32_e32 v26, 16, v0
	v_and_b32_e32 v0, 0xffff0000, v0
	v_lshlrev_b32_e32 v29, 16, v3
	v_and_b32_e32 v1, 0xffff0000, v1
	v_and_b32_e32 v3, 0xffff0000, v3
	s_waitcnt vmcnt(1)
	v_lshlrev_b32_e32 v25, 16, v47
	v_lshlrev_b32_e32 v24, 16, v46
	s_waitcnt vmcnt(0)
	v_lshlrev_b32_e32 v55, 16, v51
	v_lshlrev_b32_e32 v54, 16, v50
	v_and_b32_e32 v47, 0xffff0000, v47
	v_and_b32_e32 v46, 0xffff0000, v46
	v_and_b32_e32 v51, 0xffff0000, v51
	v_and_b32_e32 v50, 0xffff0000, v50
	v_lshlrev_b32_e32 v67, 16, v49
	v_lshlrev_b32_e32 v66, 16, v48
	v_lshlrev_b32_e32 v69, 16, v53
	v_lshlrev_b32_e32 v68, 16, v52
	v_and_b32_e32 v49, 0xffff0000, v49
	v_and_b32_e32 v48, 0xffff0000, v48
	v_and_b32_e32 v53, 0xffff0000, v53
	v_and_b32_e32 v52, 0xffff0000, v52
	v_pk_fma_f32 v[24:25], v[8:9], v[54:55], v[24:25]
	v_pk_fma_f32 v[46:47], v[10:11], v[50:51], v[46:47]
	v_pk_fma_f32 v[50:51], v[6:7], v[68:69], v[66:67]
	v_pk_fma_f32 v[48:49], v[12:13], v[52:53], v[48:49]
	v_pk_mul_f32 v[24:25], v[24:25], v[56:57]
	v_pk_mul_f32 v[50:51], v[50:51], v[70:71]
	v_pk_mul_f32 v[48:49], v[48:49], v[64:65]
	v_pk_mul_f32 v[46:47], v[46:47], v[62:63]
	v_pk_mul_f32 v[24:25], v[24:25], v[90:91]
	v_pk_mul_f32 v[50:51], v[50:51], v[94:95]
	v_pk_mul_f32 v[48:49], v[48:49], v[96:97]
	v_pk_mul_f32 v[46:47], v[46:47], v[92:93]
	v_bfe_u32 v28, v49, 16, 1
	v_bfe_u32 v55, v24, 16, 1
	v_bfe_u32 v56, v25, 16, 1
	v_bfe_u32 v57, v50, 16, 1
	v_bfe_u32 v62, v51, 16, 1
	v_bfe_u32 v52, v48, 16, 1
	v_bfe_u32 v53, v47, 16, 1
	v_bfe_u32 v54, v46, 16, 1
	v_add3_u32 v28, v49, v28, s33
	v_add3_u32 v49, v51, v62, s33
	v_add3_u32 v50, v50, v57, s33
	v_add3_u32 v25, v25, v56, s33
	v_add3_u32 v24, v24, v55, s33
	v_add3_u32 v46, v46, v54, s33
	v_add3_u32 v47, v47, v53, s33
	v_add3_u32 v48, v48, v52, s33
	v_lshrrev_b32_e32 v24, 16, v24
	v_lshrrev_b32_e32 v25, 16, v25
	v_lshrrev_b32_e32 v50, 16, v50
	v_lshrrev_b32_e32 v49, 16, v49
	v_and_or_b32 v49, v28, s29, v49
	v_and_or_b32 v48, v48, s29, v50
	v_and_or_b32 v47, v47, s29, v25
	v_and_or_b32 v46, v46, s29, v24
	global_store_dwordx4 v[42:43], v[46:49], off
	global_load_dwordx4 v[46:49], v[30:31], off nt
	s_nop 0
	global_load_dwordx4 v[50:53], v[40:41], off nt
	s_waitcnt vmcnt(1)
	v_lshlrev_b32_e32 v25, 16, v47
	v_lshlrev_b32_e32 v24, 16, v46
	s_waitcnt vmcnt(0)
; __device__ __forceinline__ float bf2f(unsigned h) { return __uint_as_float(h << 16); }
; __device__ __forceinline__ unsigned pk2(float lo, float hi) { return f2bf(lo) | (f2bf(hi) << 16); }
; __device__ __forceinline__ float sigmf(float x) { return __builtin_amdgcn_rcpf(1.0f + __expf(-x)); }
; __device__ __forceinline__ void rg_b_unit(const Params& p, int unit) {
;     ...
; #pragma unroll 4
;     for (int tq = 0; tq < 8; ++tq) { const int t = 8 * tq + r8; const size_t o = (size_t)(n * 64 + t) * D;
;         const u32x4 hv = __builtin_nontemporal_load((const u32x4*)(HL + o)), pv = __builtin_nontemporal_load((const u32x4*)(PC + o)), gv = __builtin_nontemporal_load((const u32x4*)(Z + (size_t)t * ZW + 1024)); u32x4 ov;
; #pragma unroll
;         for (int c = 0; c < 4; ++c) { const float h0 = bf2f(hv[c] & 0xffffu) + bf2f(pv[c] & 0xffffu) * carry[2 * c], h1 = bf2f(hv[c] >> 16) + bf2f(pv[c] >> 16) * carry[2 * c + 1];
;             const float g0 = bf2f(gv[c] & 0xffffu), g1 = bf2f(gv[c] >> 16); ov[c] = pk2(h0 * g0 * sigmf(g0), h1 * g1 * sigmf(g1)); }
;         *(u32x4*)(Z + (size_t)t * ZW) = ov; }
; __global__ void __launch_bounds__(NT, 2) mk_fwd(Params p) {
;     ...
;     for (int u = bid; u < 512; u += G) rg_b_unit(p, u);
	v_lshlrev_b32_e32 v31, 16, v51
	v_lshlrev_b32_e32 v30, 16, v50
	v_and_b32_e32 v41, 0xffff0000, v47
	v_and_b32_e32 v40, 0xffff0000, v46
	v_and_b32_e32 v43, 0xffff0000, v51
	v_and_b32_e32 v42, 0xffff0000, v50
	v_lshlrev_b32_e32 v47, 16, v49
	v_lshlrev_b32_e32 v46, 16, v48
	v_lshlrev_b32_e32 v51, 16, v53
	v_lshlrev_b32_e32 v50, 16, v52
	v_and_b32_e32 v49, 0xffff0000, v49
	v_and_b32_e32 v48, 0xffff0000, v48
	v_and_b32_e32 v53, 0xffff0000, v53
	v_and_b32_e32 v52, 0xffff0000, v52
	v_pk_fma_f32 v[24:25], v[8:9], v[30:31], v[24:25]
	v_pk_fma_f32 v[30:31], v[10:11], v[42:43], v[40:41]
	v_pk_fma_f32 v[40:41], v[6:7], v[50:51], v[46:47]
	v_pk_fma_f32 v[42:43], v[12:13], v[52:53], v[48:49]
	v_pk_mul_f32 v[24:25], v[24:25], v[74:75]
	v_pk_mul_f32 v[40:41], v[40:41], v[78:79]
	v_pk_mul_f32 v[30:31], v[30:31], v[76:77]
	v_pk_mul_f32 v[42:43], v[42:43], v[80:81]
	v_pk_mul_f32 v[24:25], v[24:25], v[58:59]
	v_pk_mul_f32 v[40:41], v[40:41], v[72:73]
	v_pk_mul_f32 v[30:31], v[30:31], v[60:61]
	v_pk_mul_f32 v[42:43], v[42:43], v[82:83]
	v_bfe_u32 v49, v24, 16, 1
	v_bfe_u32 v50, v25, 16, 1
	v_bfe_u32 v51, v40, 16, 1
	v_bfe_u32 v52, v41, 16, 1
	v_bfe_u32 v28, v43, 16, 1
	v_bfe_u32 v46, v42, 16, 1
	v_bfe_u32 v47, v31, 16, 1
	v_bfe_u32 v48, v30, 16, 1
	v_add3_u32 v41, v41, v52, s33
	v_add3_u32 v40, v40, v51, s33
	v_add3_u32 v25, v25, v50, s33
	v_add3_u32 v24, v24, v49, s33
	v_add3_u32 v30, v30, v48, s33
	v_add3_u32 v31, v31, v47, s33
	v_add3_u32 v42, v42, v46, s33
	v_add3_u32 v28, v43, v28, s33
	v_lshrrev_b32_e32 v24, 16, v24
	v_lshrrev_b32_e32 v25, 16, v25
	v_lshrrev_b32_e32 v40, 16, v40
	v_lshrrev_b32_e32 v41, 16, v41
	v_and_or_b32 v43, v28, s29, v41
	v_and_or_b32 v42, v42, s29, v40
	v_and_or_b32 v41, v31, s29, v25
	v_and_or_b32 v40, v30, s29, v24
	global_store_dwordx4 v[38:39], v[40:43], off
	global_load_dwordx4 v[38:41], v[32:33], off nt
	s_nop 0
	global_load_dwordx4 v[46:49], v[36:37], off nt
	v_lshlrev_b32_e32 v28, 16, v2
	v_and_b32_e32 v2, 0xffff0000, v2
	v_mul_f32_e32 v24, 0xbfb8aa3b, v26
	v_mul_f32_e32 v25, 0xbfb8aa3b, v0
	v_mul_f32_e32 v30, 0xbfb8aa3b, v27
	v_mul_f32_e32 v32, 0xbfb8aa3b, v28
	v_mul_f32_e32 v33, 0xbfb8aa3b, v2
	v_mul_f32_e32 v36, 0xbfb8aa3b, v29
	v_mul_f32_e32 v31, 0xbfb8aa3b, v1
	v_mul_f32_e32 v37, 0xbfb8aa3b, v3
	v_exp_f32_e32 v24, v24
	v_exp_f32_e32 v25, v25
	v_exp_f32_e32 v30, v30
	v_exp_f32_e32 v32, v32
	v_exp_f32_e32 v33, v33
	v_exp_f32_e32 v36, v36
	v_exp_f32_e32 v31, v31
	v_exp_f32_e32 v37, v37
	v_add_f32_e32 v24, 1.0, v24
	v_add_f32_e32 v25, 1.0, v25
	v_add_f32_e32 v42, 1.0, v30
	v_add_f32_e32 v32, 1.0, v32
	v_add_f32_e32 v33, 1.0, v33
	v_add_f32_e32 v43, 1.0, v36
	v_add_f32_e32 v31, 1.0, v31
	v_add_f32_e32 v37, 1.0, v37
	v_rcp_f32_e32 v24, v24
	v_rcp_f32_e32 v30, v25
	v_rcp_f32_e32 v25, v42
	v_rcp_f32_e32 v32, v32
	v_rcp_f32_e32 v36, v33
	v_rcp_f32_e32 v33, v43
	v_rcp_f32_e32 v31, v31
	v_rcp_f32_e32 v37, v37
	s_waitcnt vmcnt(1)
	v_lshlrev_b32_e32 v43, 16, v39
	v_lshlrev_b32_e32 v42, 16, v38
	s_waitcnt vmcnt(0)
	v_lshlrev_b32_e32 v51, 16, v47
	v_lshlrev_b32_e32 v50, 16, v46
	v_and_b32_e32 v39, 0xffff0000, v39
	v_and_b32_e32 v38, 0xffff0000, v38
	v_and_b32_e32 v47, 0xffff0000, v47
	v_and_b32_e32 v46, 0xffff0000, v46
	v_lshlrev_b32_e32 v53, 16, v41
	v_lshlrev_b32_e32 v52, 16, v40
	v_lshlrev_b32_e32 v55, 16, v49
	v_lshlrev_b32_e32 v54, 16, v48
	v_and_b32_e32 v41, 0xffff0000, v41
	v_and_b32_e32 v40, 0xffff0000, v40
	v_and_b32_e32 v49, 0xffff0000, v49
	v_and_b32_e32 v48, 0xffff0000, v48
	v_pk_fma_f32 v[42:43], v[8:9], v[50:51], v[42:43]
	v_pk_fma_f32 v[38:39], v[10:11], v[46:47], v[38:39]
	v_pk_fma_f32 v[46:47], v[6:7], v[54:55], v[52:53]
	v_pk_fma_f32 v[40:41], v[12:13], v[48:49], v[40:41]
	v_pk_mul_f32 v[26:27], v[42:43], v[26:27]
	v_pk_mul_f32 v[28:29], v[46:47], v[28:29]
	v_pk_mul_f32 v[0:1], v[38:39], v[0:1]
	v_pk_mul_f32 v[2:3], v[40:41], v[2:3]
	v_pk_mul_f32 v[24:25], v[26:27], v[24:25]
	v_pk_mul_f32 v[26:27], v[28:29], v[32:33]
	v_pk_mul_f32 v[0:1], v[0:1], v[30:31]
	v_pk_mul_f32 v[2:3], v[2:3], v[36:37]
	v_bfe_u32 v32, v24, 16, 1
	v_bfe_u32 v33, v25, 16, 1
	v_bfe_u32 v36, v26, 16, 1
	v_bfe_u32 v37, v27, 16, 1
	v_bfe_u32 v28, v3, 16, 1
	v_bfe_u32 v29, v2, 16, 1
	v_bfe_u32 v30, v1, 16, 1
	v_bfe_u32 v31, v0, 16, 1
	v_add3_u32 v27, v27, v37, s33
	v_add3_u32 v26, v26, v36, s33
	v_add3_u32 v25, v25, v33, s33
	v_add3_u32 v24, v24, v32, s33
	v_add3_u32 v0, v0, v31, s33
	v_add3_u32 v1, v1, v30, s33
	v_add3_u32 v2, v2, v29, s33
	v_add3_u32 v3, v3, v28, s33
	v_lshrrev_b32_e32 v24, 16, v24
	v_lshrrev_b32_e32 v25, 16, v25
	v_lshrrev_b32_e32 v26, 16, v26
	v_lshrrev_b32_e32 v27, 16, v27
	v_and_or_b32 v3, v3, s29, v27
	v_and_or_b32 v2, v2, s29, v26
	v_and_or_b32 v1, v1, s29, v25
	v_and_or_b32 v0, v0, s29, v24
	global_store_dwordx4 v[34:35], v[0:3], off
	s_cbranch_scc1 .LBB0_218
	s_add_i32 s37, s37, s52
	s_xor_b32 s37, s37, 0x7e
	s_add_i32 s25, s25, s26
	s_cmpk_gt_i32 s37, 0x1ff
	s_cbranch_scc0 .LBB0_209
	s_nop 0
